# passA chunk loop: K-tile bf16 2x2 transposes via v_perm_b32; V^T staging reads its eight e_s weights once (two ds_read_b128) and uses packed multiplies
# speedup vs baseline: 1.0259x; 1.0099x over previous
; __device__ void passA(const Params& p, LAS unsigned char* lds, int wg) {
;     ...
;     { bool ic; int ci; const bf16_t* Kb; const bf16_t* Vb; passA_chunk(p, 0, b, h, dir, vs, ic, ci, Kb, Vb);
; #pragma unroll
;         for (int rep = 0; rep < 2; ++rep) { const int it = tid + rep * 512;
;             vr[rep] = *(const u32x4*)(Vb + (size_t)it * 8);
;             const int sq = (it & 15) | (((it >> 6) & 1) << 4), ko = ((it >> 4) & 3) | ((it >> 7) << 2); const bf16_t* src = Kb + (size_t)((sq >> 2) * 8 + (ko >> 2)) * 512 + ((sq & 3) * 16 + (ko & 3)) * 8;
;             kr[rep][0] = *(const u32x4*)src; kr[rep][1] = *(const u32x4*)(src + 32); kr[rep][2] = *(const u32x4*)(src + 64); kr[rep][3] = *(const u32x4*)(src + 96); } }
;     for (int st = 0; st < 18; ++st) {
;         bool isctx; int ci; const bf16_t* Kb; const bf16_t* Vb; passA_chunk(p, st, b, h, dir, vs, isctx, ci, Kb, Vb);
;         if (!isctx) {
;             bf16_t* cs = cst_ptr(p, sid, ci);
; #pragma unroll
;             for (int vt = 0; vt < 4; ++vt) { u32x4 w; w.x = cvt_pk_bf16(acc[0][vt][0], acc[0][vt][1]); w.y = cvt_pk_bf16(acc[0][vt][2], acc[0][vt][3]);
;                 w.z = cvt_pk_bf16(acc[1][vt][0], acc[1][vt][1]); w.w = cvt_pk_bf16(acc[1][vt][2], acc[1][vt][3]);
;                 __builtin_nontemporal_store(w, (u32x4*)(cs + (size_t)((vs * 4 + vt) * 8 + wid) * 512 + (fr * 4 + fq) * 8)); }
;             if (vs == 0) { if (fr == 0) { float* np = (float*)(p.ws + OFF_NST) + (size_t)(sid * 16 + ci) * 256 + wid * 32 + fq * 8; *(f32x4*)np = nacc[0]; *(f32x4*)(np + 4) = nacc[1]; }
;                 if (tid == 0) ((float*)(p.ws + OFF_MST))[sid * 16 + ci] = mprevA[st]; }
;         }
;         if (st == 17) break;
;         const LAS float* e_s = eA + st * 128; const float decay = decayA[st];
; #pragma unroll
;         for (int rep = 0; rep < 2; ++rep) { const int it = tid + rep * 512; const int v = (it >> 8) * 16 + ((it >> 2) & 15), sg = ((it >> 6) & 3) * 32 + (it & 3) * 8;
;             const u32x4 raw = vr[rep];
;             u32x4 w; w.x = cvt_pk_bf16(bf_lo(raw.x) * e_s[sg], bf_hi(raw.x) * e_s[sg + 1]); w.y = cvt_pk_bf16(bf_lo(raw.y) * e_s[sg + 2], bf_hi(raw.y) * e_s[sg + 3]);
;             w.z = cvt_pk_bf16(bf_lo(raw.z) * e_s[sg + 4], bf_hi(raw.z) * e_s[sg + 5]); w.w = cvt_pk_bf16(bf_lo(raw.w) * e_s[sg + 6], bf_hi(raw.w) * e_s[sg + 7]);
;             *(LAS u32x4*)(Ve + v * 136 + sg) = w; }
; #pragma unroll
.Lgb2_done:
	s_or_b64 exec, exec, s[12:13]
	s_waitcnt lgkmcnt(0)
	s_barrier
	global_load_dwordx4 v[10:13], v[0:1], off
	v_add_u32_e32 v6, 0x200, v4
	v_ashrrev_i32_e32 v7, 31, v6
	v_and_b32_e32 v100, 15, v4
	v_lshrrev_b32_e32 v0, 2, v4
	v_bfe_u32 v48, v4, 4, 2
	v_lshlrev_b32_e32 v1, 4, v4
	v_lshlrev_b64 v[84:85], 4, v[6:7]
	v_and_or_b32 v3, v0, 16, v100
	v_and_or_b32 v5, v1, 48, v48
	v_lshl_add_u64 v[0:1], s[6:7], 0, v[84:85]
	global_load_dwordx4 v[14:17], v[0:1], off
	v_mov_b32_e32 v83, 0
	v_lshlrev_b32_e32 v0, 1, v3
	v_lshlrev_b32_e32 v82, 4, v5
	v_lshlrev_b32_e32 v9, 3, v4
	v_ashrrev_i32_e32 v2, 7, v4
	v_and_b32_e32 v5, 56, v0
	v_lshl_add_u64 v[18:19], s[0:1], 0, v[82:83]
	v_lshrrev_b32_e32 v57, 1, v4
	s_movk_i32 s1, 0x60
	v_and_b32_e32 v9, 24, v9
	v_add_u32_e32 v0, v5, v2
	v_and_b32_e32 v50, 60, v8
	v_ashrrev_i32_e32 v8, 7, v6
	v_and_or_b32 v52, v57, s1, v9
	v_ashrrev_i32_e32 v1, 31, v0
	v_lshl_add_u32 v9, v52, 2, 0
	v_add_u32_e32 v8, v5, v8
	v_lshlrev_b64 v[86:87], 10, v[0:1]
	v_add_u32_e32 v91, 0x15400, v9
	v_ashrrev_i32_e32 v9, 31, v8
	v_lshl_add_u64 v[34:35], v[18:19], 0, v[86:87]
	v_lshlrev_b64 v[88:89], 10, v[8:9]
	global_load_dwordx4 v[0:3], v[34:35], off offset:192
	v_lshl_add_u64 v[8:9], v[18:19], 0, v[88:89]
	global_load_dwordx4 v[18:21], v[34:35], off offset:64
	global_load_dwordx4 v[22:25], v[34:35], off offset:128
	global_load_dwordx4 v[26:29], v[8:9], off
	global_load_dwordx4 v[30:33], v[8:9], off offset:64
	s_lshl_b32 s29, s29, 2
	global_load_dwordx4 v[34:37], v[34:35], off
	s_and_b32 s38, s29, 0x1f0
	s_cmp_eq_u32 s34, 0
	s_cselect_b64 s[6:7], -1, 0
	s_add_i32 s1, 0, 0x17900
	v_mov_b32_e32 v5, s1
	ds_read_b32 v53, v5
	ds_read_b64 v[46:47], v91
	global_load_dwordx4 v[38:41], v[8:9], off offset:128
	global_load_dwordx4 v[42:45], v[8:9], off offset:192
	v_lshrrev_b32_e32 v7, 4, v4
	v_bfe_u32 v49, v4, 2, 4
	s_mov_b32 s9, 0xffffff0
	v_and_b32_e32 v51, 64, v4
	s_movk_i32 s0, 0x110
	v_and_or_b32 v7, v7, s9, v49
	s_add_i32 s1, 0, 0x11000
	v_mul_lo_u32 v7, v7, s0
	v_lshlrev_b32_e32 v111, 1, v4
	v_lshlrev_b32_e32 v90, 5, v56
	v_and_b32_e32 v112, 3, v4
	v_and_b32_e32 v105, 48, v4
	v_add_u32_e32 v113, s1, v105
	v_lshrrev_b32_e32 v4, 5, v4
	s_mov_b32 s39, 0xffff0000
	s_xor_b32 s8, s8, 1
	v_readlane_b32 s16, v254, 31
	v_readlane_b32 s17, v254, 32
	v_lshl_add_u64 v[102:103], s[30:31], 0, v[82:83]
	s_mov_b32 s40, 0
	s_waitcnt vmcnt(9)
	v_and_b32_e32 v8, 0xffff0000, v10
	v_lshlrev_b32_e32 v5, 16, v10
	s_waitcnt lgkmcnt(0)
	v_mul_f32_e32 v8, v47, v8
	v_mul_f32_e32 v5, v46, v5
	v_cvt_pk_bf16_f32 v8, v5, v8
	ds_read_b64 v[46:47], v91 offset:8
	v_lshlrev_b32_e32 v9, 16, v11
	v_and_b32_e32 v10, 0xffff0000, v11
	v_lshlrev_b32_e32 v5, 1, v51
	v_lshl_add_u32 v51, v52, 1, s1
	s_waitcnt lgkmcnt(0)
	v_mul_f32_e32 v9, v46, v9
	v_mul_f32_e32 v10, v47, v10
	v_cvt_pk_bf16_f32 v9, v9, v10
	ds_read_b64 v[10:11], v91 offset:16
	v_lshlrev_b32_e32 v46, 16, v12
	v_and_b32_e32 v12, 0xffff0000, v12
	v_add_u32_e32 v106, v51, v7
	v_lshlrev_b32_e32 v7, 16, v13
	s_waitcnt lgkmcnt(0)
	v_mul_f32_e32 v10, v10, v46
	v_mul_f32_e32 v11, v11, v12
	v_cvt_pk_bf16_f32 v10, v10, v11
	ds_read_b64 v[46:47], v91 offset:24
	v_and_b32_e32 v11, 0xffff0000, v13
	v_and_b32_e32 v12, 24, v111
	s_mov_b32 s1, 0x1fffffc
	v_and_or_b32 v4, v4, s1, v48
	s_waitcnt lgkmcnt(0)
	v_mul_f32_e32 v11, v47, v11
	v_mul_f32_e32 v7, v46, v7
	v_cvt_pk_bf16_f32 v11, v7, v11
	ds_write_b128 v106, v[8:11]
	ds_read_b64 v[8:9], v91
	s_waitcnt vmcnt(8)
	v_lshlrev_b32_e32 v10, 16, v14
	v_and_b32_e32 v11, 0xffff0000, v14
	v_lshlrev_b32_e32 v7, 1, v50
	v_add3_u32 v7, 0, v5, v7
	s_waitcnt lgkmcnt(0)
	v_mul_f32_e32 v8, v8, v10
	v_mul_f32_e32 v9, v9, v11
	v_cvt_pk_bf16_f32 v8, v8, v9
	ds_read_b64 v[10:11], v91 offset:8
	v_and_b32_e32 v9, 0xffff0000, v15
	v_lshlrev_b32_e32 v5, 16, v15
	v_or3_b32 v14, v112, v12, v90
	v_and_b32_e32 v12, 0xffff0000, v16
	s_waitcnt lgkmcnt(0)
	v_mul_f32_e32 v9, v11, v9
	v_mul_f32_e32 v5, v10, v5
	v_cvt_pk_bf16_f32 v9, v5, v9
	ds_read_b64 v[10:11], v91 offset:16
	v_lshlrev_b32_e32 v5, 16, v16
	v_add_u32_e32 v46, 0, v105
	s_waitcnt lgkmcnt(0)
	v_mul_f32_e32 v5, v10, v5
	v_mul_f32_e32 v10, v11, v12
	v_cvt_pk_bf16_f32 v10, v5, v10
	ds_read_b64 v[12:13], v91 offset:24
	v_lshrrev_b32_e32 v5, 4, v6
	v_and_or_b32 v5, v5, s9, v49
	v_lshlrev_b32_e32 v11, 16, v17
	v_mul_lo_u32 v5, v5, s0
	s_movk_i32 s9, 0x880
	s_waitcnt lgkmcnt(0)
	v_mul_f32_e32 v11, v12, v11
	v_and_b32_e32 v12, 0xffff0000, v17
	v_add_u32_e32 v107, v51, v5
	v_mul_lo_u32 v4, v4, s9
	v_mul_f32_e32 v12, v13, v12
	v_cvt_pk_bf16_f32 v11, v11, v12
	ds_write_b128 v107, v[8:11]
	v_add_u32_e32 v108, v7, v4
	s_waitcnt vmcnt(2)
	v_and_b32_e32 v4, 0xffff, v34
	v_and_b32_e32 v5, 0xffff, v22
	v_lshrrev_b32_e32 v8, 16, v34
	v_lshrrev_b32_e32 v9, 16, v22
	v_lshl_or_b32 v4, v18, 16, v4
	v_lshl_or_b32 v5, v0, 16, v5
	v_and_or_b32 v8, v18, s39, v8
	v_and_or_b32 v9, v0, s39, v9
	v_and_b32_e32 v0, 0xffff, v35
	ds_write2_b64 v108, v[4:5], v[8:9] offset1:34
	v_lshl_or_b32 v4, v19, 16, v0
	v_and_b32_e32 v0, 0xffff, v23
	v_lshl_or_b32 v5, v1, 16, v0
	v_lshrrev_b32_e32 v0, 16, v35
	v_lshrrev_b32_e32 v8, 16, v23
	v_and_or_b32 v0, v19, s39, v0
	v_and_or_b32 v1, v1, s39, v8
	ds_write2_b64 v108, v[4:5], v[0:1] offset0:68 offset1:102
	v_and_b32_e32 v0, 0xffff, v36
	v_and_b32_e32 v1, 0xffff, v24
	v_lshrrev_b32_e32 v4, 16, v36
	v_lshrrev_b32_e32 v5, 16, v24
	v_lshl_or_b32 v0, v20, 16, v0
	v_lshl_or_b32 v1, v2, 16, v1
	v_and_or_b32 v4, v20, s39, v4
	v_and_or_b32 v5, v2, s39, v5
	ds_write2_b64 v108, v[0:1], v[4:5] offset0:136 offset1:170
	v_and_b32_e32 v0, 0xffff, v37
	v_and_b32_e32 v1, 0xffff, v25
	v_lshrrev_b32_e32 v2, 16, v37
	v_lshrrev_b32_e32 v4, 16, v25
	v_lshl_or_b32 v0, v21, 16, v0
	v_lshl_or_b32 v1, v3, 16, v1
	v_and_or_b32 v2, v21, s39, v2
	v_and_or_b32 v3, v3, s39, v4
	ds_write2_b64 v108, v[0:1], v[2:3] offset0:204 offset1:238
	v_lshrrev_b32_e32 v0, 5, v6
	v_and_or_b32 v0, v0, s1, v48
	v_mul_lo_u32 v0, v0, s9
	v_add_u32_e32 v109, v7, v0
	v_and_b32_e32 v0, 0xffff, v26
	s_waitcnt vmcnt(1)
; __device__ void passA(const Params& p, LAS unsigned char* lds, int wg) {
;     ...
;         for (int rep = 0; rep < 2; ++rep) { const int it = tid + rep * 512; const int sq = (it & 15) | (((it >> 6) & 1) << 4), ko = ((it >> 4) & 3) | ((it >> 7) << 2);
;             const u32x4 r0 = kr[rep][0], r1 = kr[rep][1], r2 = kr[rep][2], r3 = kr[rep][3];
;             LAS bf16_t* dst = Kt + (ko * 8) * 136 + sq * 4;
;     ...
;             TRW(0, r0.x, r1.x, r2.x, r3.x, 0) TRW(1, r0.x, r1.x, r2.x, r3.x, 1) TRW(2, r0.y, r1.y, r2.y, r3.y, 0) TRW(3, r0.y, r1.y, r2.y, r3.y, 1)
;             TRW(4, r0.z, r1.z, r2.z, r3.z, 0) TRW(5, r0.z, r1.z, r2.z, r3.z, 1) TRW(6, r0.w, r1.w, r2.w, r3.w, 0) TRW(7, r0.w, r1.w, r2.w, r3.w, 1)
;     ...
;         }
;         __syncthreads();
;         if (st + 1 < 17) {
;             bool ic2; int ci2; const bf16_t* Kb2; const bf16_t* Vb2; passA_chunk(p, st + 1, b, h, dir, vs, ic2, ci2, Kb2, Vb2);
; #pragma unroll
;             for (int rep = 0; rep < 2; ++rep) { const int it = tid + rep * 512;
;                 vr[rep] = *(const u32x4*)(Vb2 + (size_t)it * 8);
;                 const int sq = (it & 15) | (((it >> 6) & 1) << 4), ko = ((it >> 4) & 3) | ((it >> 7) << 2); const bf16_t* src = Kb2 + (size_t)((sq >> 2) * 8 + (ko >> 2)) * 512 + ((sq & 3) * 16 + (ko & 3)) * 8;
;                 kr[rep][0] = *(const u32x4*)src; kr[rep][1] = *(const u32x4*)(src + 32); kr[rep][2] = *(const u32x4*)(src + 64); kr[rep][3] = *(const u32x4*)(src + 96); } }
; #pragma unroll
;         for (int a = 0; a < 2; ++a) { nacc[a] *= decay;
; #pragma unroll
;             for (int v = 0; v < 4; ++v) acc[a][v] *= decay; }
; #pragma unroll
;         for (int ks = 0; ks < 4; ++ks) { bf16x8 kf[2], vf[4];
; #pragma unroll
;             for (int kt = 0; kt < 2; ++kt) kf[kt] = *(const LAS bf16x8*)(Kt + (wid * 32 + 8 * (fr >> 2) + 4 * kt + (fr & 3)) * 136 + ks * 32 + fq * 8);
; #pragma unroll
;             for (int vt = 0; vt < 4; ++vt) vf[vt] = *(const LAS bf16x8*)(Ve + (vt * 16 + fr) * 136 + ks * 32 + fq * 8);
;             bf16x8 ef = *(const LAS bf16x8*)(eB + st * 128 + ks * 32 + fq * 8);
;             if (fr != 0) ef = (bf16x8){0, 0, 0, 0, 0, 0, 0, 0};
; #pragma unroll
;             for (int kt = 0; kt < 2; ++kt) {
; #pragma unroll
;                 for (int vt = 0; vt < 4; ++vt) acc[kt][vt] = __builtin_amdgcn_mfma_f32_16x16x32_bf16(kf[kt], vf[vt], acc[kt][vt], 0, 0, 0);
	v_and_b32_e32 v1, 0xffff, v38
	v_lshrrev_b32_e32 v2, 16, v26
	v_lshrrev_b32_e32 v3, 16, v38
	v_lshl_or_b32 v0, v30, 16, v0
	s_waitcnt vmcnt(0)
	v_lshl_or_b32 v1, v42, 16, v1
	v_and_or_b32 v2, v30, s39, v2
	v_and_or_b32 v3, v42, s39, v3
	ds_write2_b64 v109, v[0:1], v[2:3] offset1:34
	v_and_b32_e32 v0, 0xffff, v27
	v_and_b32_e32 v1, 0xffff, v39
	v_lshrrev_b32_e32 v2, 16, v27
	v_lshrrev_b32_e32 v3, 16, v39
	v_lshl_or_b32 v0, v31, 16, v0
	v_lshl_or_b32 v1, v43, 16, v1
	v_and_or_b32 v2, v31, s39, v2
	v_and_or_b32 v3, v43, s39, v3
	ds_write2_b64 v109, v[0:1], v[2:3] offset0:68 offset1:102
	v_and_b32_e32 v0, 0xffff, v28
	v_and_b32_e32 v1, 0xffff, v40
	v_lshrrev_b32_e32 v2, 16, v28
	v_lshrrev_b32_e32 v3, 16, v40
	v_lshl_or_b32 v0, v32, 16, v0
	v_lshl_or_b32 v1, v44, 16, v1
	v_and_or_b32 v2, v32, s39, v2
	v_and_or_b32 v3, v44, s39, v3
	ds_write2_b64 v109, v[0:1], v[2:3] offset0:136 offset1:170
	v_and_b32_e32 v0, 0xffff, v29
	v_and_b32_e32 v1, 0xffff, v41
	v_lshrrev_b32_e32 v2, 16, v29
	v_lshrrev_b32_e32 v3, 16, v41
	v_lshl_or_b32 v0, v33, 16, v0
	v_lshl_or_b32 v1, v45, 16, v1
	v_and_or_b32 v2, v33, s39, v2
	v_and_or_b32 v3, v45, s39, v3
	ds_write2_b64 v109, v[0:1], v[2:3] offset0:204 offset1:238
	v_mul_lo_u32 v1, v14, s0
	v_add_u32_e32 v110, v46, v1
	s_waitcnt lgkmcnt(0)
	s_barrier
	ds_read_b128 v[4:7], v110
	v_mad_u32_u24 v29, v100, s0, v113
	ds_read_b128 v[8:11], v29
	v_add_u32_e32 v30, 0x17a80, v46
	v_mul_f32_e32 v0, 0, v53
	ds_read_b128 v[12:15], v29 offset:4352
	ds_read_b128 v[16:19], v110 offset:64
	ds_read_b128 v[20:23], v29 offset:64
	ds_read_b128 v[32:35], v29 offset:8704
	ds_read_b128 v[36:39], v29 offset:4416
	ds_read_b128 v[44:47], v29 offset:13056
	ds_read_b128 v[48:51], v30
	ds_read_b128 v[52:55], v29 offset:8768
	ds_read_b128 v[62:65], v30 offset:64
	ds_read_b128 v[66:69], v29 offset:13120
	ds_read_b128 v[74:77], v110 offset:1088
	ds_read_b128 v[92:95], v110 offset:1152
	v_mov_b32_e32 v1, v0
	v_mov_b32_e32 v2, v0
	v_mov_b32_e32 v3, v0
	s_lshl_b32 s9, s8, 2
	s_or_b32 s12, s9, s25
	s_waitcnt lgkmcnt(12)
	v_mfma_f32_16x16x32_bf16 v[24:27], v[4:7], v[8:11], v[0:3]
	v_cmp_eq_u32_e64 s[0:1], 0, v100
	s_ashr_i32 s13, s12, 31
	s_lshl_b64 s[12:13], s[12:13], 16
	s_waitcnt lgkmcnt(1)
	v_mfma_f32_16x16x32_bf16 v[8:11], v[74:77], v[8:11], v[0:3]
	v_cndmask_b32_e64 v51, 0, v51, s[0:1]
	v_cndmask_b32_e64 v50, 0, v50, s[0:1]
	v_cndmask_b32_e64 v49, 0, v49, s[0:1]
	v_mfma_f32_16x16x32_bf16 v[40:43], v[4:7], v[12:15], v[0:3]
	v_cndmask_b32_e64 v48, 0, v48, s[0:1]
	s_add_u32 s12, s11, s12
	s_addc_u32 s13, s14, s13
	v_mfma_f32_16x16x32_bf16 v[12:15], v[74:77], v[12:15], v[0:3]
	s_ashr_i32 s9, s8, 31
	s_lshl_b64 s[8:9], s[8:9], 18
	s_add_u32 s3, s3, s8
	v_mfma_f32_16x16x32_bf16 v[24:27], v[16:19], v[20:23], v[24:27]
	s_addc_u32 s9, s27, s9
	s_add_u32 s8, s3, s10
	s_addc_u32 s9, s9, 0
	s_waitcnt lgkmcnt(0)
	v_mfma_f32_16x16x32_bf16 v[8:11], v[92:95], v[20:23], v[8:11]
	ds_read_b128 v[20:23], v110 offset:128
	v_lshl_add_u64 v[78:79], s[8:9], 0, v[84:85]
	s_add_i32 s3, 0, 0x17904
	v_mfma_f32_16x16x32_bf16 v[58:61], v[4:7], v[32:35], v[0:3]
	s_cmp_eq_u32 s28, 0
	s_mov_b32 s27, 2
	s_mov_b32 s28, 14
	v_mfma_f32_16x16x32_bf16 v[70:73], v[4:7], v[44:47], v[0:3]
	v_mfma_f32_16x16x32_bf16 v[4:7], v[4:7], v[48:51], v[0:3]
	v_mfma_f32_16x16x32_bf16 v[32:35], v[74:77], v[32:35], v[0:3]
	v_mfma_f32_16x16x32_bf16 v[44:47], v[74:77], v[44:47], v[0:3]
	v_mfma_f32_16x16x32_bf16 v[0:3], v[74:77], v[48:51], v[0:3]
	v_mfma_f32_16x16x32_bf16 v[40:43], v[16:19], v[36:39], v[40:43]
	v_mfma_f32_16x16x32_bf16 v[12:15], v[92:95], v[36:39], v[12:15]
	ds_read_b128 v[36:39], v29 offset:128
	v_mfma_f32_16x16x32_bf16 v[48:51], v[16:19], v[52:55], v[58:61]
	s_nop 2
	v_cndmask_b32_e64 v61, 0, v65, s[0:1]
	v_cndmask_b32_e64 v60, 0, v64, s[0:1]
	v_cndmask_b32_e64 v59, 0, v63, s[0:1]
	v_cndmask_b32_e64 v58, 0, v62, s[0:1]
	v_mfma_f32_16x16x32_bf16 v[70:73], v[16:19], v[66:69], v[70:73]
	s_nop 0
	v_mfma_f32_16x16x32_bf16 v[4:7], v[16:19], v[58:61], v[4:7]
	v_mfma_f32_16x16x32_bf16 v[16:19], v[92:95], v[52:55], v[32:35]
	v_mfma_f32_16x16x32_bf16 v[32:35], v[92:95], v[66:69], v[44:47]
	v_mfma_f32_16x16x32_bf16 v[0:3], v[92:95], v[58:61], v[0:3]
	s_nop 1
	ds_read_b128 v[44:47], v29 offset:4480
	ds_read_b128 v[52:55], v110 offset:192
	ds_read_b128 v[58:61], v29 offset:192
	ds_read_b128 v[62:65], v110 offset:1216
	ds_read_b128 v[66:69], v29 offset:8832
	ds_read_b128 v[74:77], v29 offset:4544
	ds_read_b128 v[92:95], v30 offset:128
	ds_read_b128 v[96:99], v29 offset:13184
	ds_read_b128 v[114:117], v29 offset:8896
	s_waitcnt lgkmcnt(9)
	v_mfma_f32_16x16x32_bf16 v[24:27], v[20:23], v[36:39], v[24:27]
	ds_read_b128 v[118:121], v30 offset:192
	ds_read_b128 v[122:125], v29 offset:13248
	s_waitcnt lgkmcnt(4)
	v_cndmask_b32_e64 v95, 0, v95, s[0:1]
	v_mfma_f32_16x16x32_bf16 v[8:11], v[62:65], v[36:39], v[8:11]
	v_lshl_add_u64 v[36:37], s[8:9], 0, v[80:81]
	global_load_dwordx4 v[36:39], v[36:37], off
	v_cndmask_b32_e64 v94, 0, v94, s[0:1]
	v_mfma_f32_16x16x32_bf16 v[40:43], v[20:23], v[44:47], v[40:43]
	v_cndmask_b32_e64 v93, 0, v93, s[0:1]
	v_cndmask_b32_e64 v92, 0, v92, s[0:1]
	s_cselect_b64 s[8:9], -1, 0
	v_mfma_f32_16x16x32_bf16 v[48:51], v[20:23], v[66:69], v[48:51]
	v_mfma_f32_16x16x32_bf16 v[12:15], v[62:65], v[44:47], v[12:15]
	v_mfma_f32_16x16x32_bf16 v[44:47], v[62:65], v[66:69], v[16:19]
	global_load_dwordx4 v[66:69], v[78:79], off
	s_waitcnt vmcnt(0)
	v_lshlrev_b32_e32 v31, 16, v68
	v_lshl_add_u64 v[16:17], s[12:13], 0, v[82:83]
	v_lshl_add_u64 v[18:19], v[16:17], 0, v[86:87]
	s_waitcnt lgkmcnt(3)
	v_mfma_f32_16x16x32_bf16 v[70:73], v[20:23], v[96:99], v[70:73]
	global_load_dwordx4 v[126:129], v[18:19], off
	s_and_b64 s[12:13], s[8:9], exec
	s_cselect_b32 s11, 0, 15
	v_mfma_f32_16x16x32_bf16 v[32:35], v[62:65], v[96:99], v[32:35]
	global_load_dwordx4 v[96:99], v[18:19], off offset:192
	v_mfma_f32_16x16x32_bf16 v[4:7], v[20:23], v[92:95], v[4:7]
	ds_read_b128 v[20:23], v110 offset:1280
	v_mfma_f32_16x16x32_bf16 v[62:65], v[62:65], v[92:95], v[0:3]
	global_load_dwordx4 v[92:95], v[18:19], off offset:64
	global_load_dwordx4 v[130:133], v[18:19], off offset:128
	s_nop 0
	v_lshl_add_u64 v[0:1], v[16:17], 0, v[88:89]
	global_load_dwordx4 v[138:141], v[0:1], off
	global_load_dwordx4 v[142:145], v[0:1], off offset:64
	global_load_dwordx4 v[146:149], v[0:1], off offset:128
	global_load_dwordx4 v[150:153], v[0:1], off offset:192
	s_waitcnt lgkmcnt(0)
	s_barrier
; #define LAS __attribute__((address_space(3)))
; __device__ void passA(const Params& p, LAS unsigned char* lds, int wg) {
;     ...
;         const LAS float* e_s = eA + st * 128; const float decay = decayA[st];
; #pragma unroll
;         for (int rep = 0; rep < 2; ++rep) { const int it = tid + rep * 512; const int v = (it >> 8) * 16 + ((it >> 2) & 15), sg = ((it >> 6) & 3) * 32 + (it & 3) * 8;
;             const u32x4 raw = vr[rep];
;             u32x4 w; w.x = cvt_pk_bf16(bf_lo(raw.x) * e_s[sg], bf_hi(raw.x) * e_s[sg + 1]); w.y = cvt_pk_bf16(bf_lo(raw.y) * e_s[sg + 2], bf_hi(raw.y) * e_s[sg + 3]);
;             w.z = cvt_pk_bf16(bf_lo(raw.z) * e_s[sg + 4], bf_hi(raw.z) * e_s[sg + 5]); w.w = cvt_pk_bf16(bf_lo(raw.w) * e_s[sg + 6], bf_hi(raw.w) * e_s[sg + 7]);
;             *(LAS u32x4*)(Ve + v * 136 + sg) = w; }
; #pragma unroll
;         for (int rep = 0; rep < 2; ++rep) { const int it = tid + rep * 512; const int sq = (it & 15) | (((it >> 6) & 1) << 4), ko = ((it >> 4) & 3) | ((it >> 7) << 2);
;             const u32x4 r0 = kr[rep][0], r1 = kr[rep][1], r2 = kr[rep][2], r3 = kr[rep][3];
;             LAS bf16_t* dst = Kt + (ko * 8) * 136 + sq * 4;
;     ...
;             TRW(0, r0.x, r1.x, r2.x, r3.x, 0) TRW(1, r0.x, r1.x, r2.x, r3.x, 1) TRW(2, r0.y, r1.y, r2.y, r3.y, 0) TRW(3, r0.y, r1.y, r2.y, r3.y, 1)
;             TRW(4, r0.z, r1.z, r2.z, r3.z, 0) TRW(5, r0.z, r1.z, r2.z, r3.z, 1) TRW(6, r0.w, r1.w, r2.w, r3.w, 0) TRW(7, r0.w, r1.w, r2.w, r3.w, 1)
;     ...
;         }
;         __syncthreads();
;         if (st + 1 < 17) {
;             bool ic2; int ci2; const bf16_t* Kb2; const bf16_t* Vb2; passA_chunk(p, st + 1, b, h, dir, vs, ic2, ci2, Kb2, Vb2);
; #pragma unroll
;             for (int rep = 0; rep < 2; ++rep) { const int it = tid + rep * 512;
;                 vr[rep] = *(const u32x4*)(Vb2 + (size_t)it * 8);
;                 const int sq = (it & 15) | (((it >> 6) & 1) << 4), ko = ((it >> 4) & 3) | ((it >> 7) << 2); const bf16_t* src = Kb2 + (size_t)((sq >> 2) * 8 + (ko >> 2)) * 512 + ((sq & 3) * 16 + (ko & 3)) * 8;
;                 kr[rep][0] = *(const u32x4*)src; kr[rep][1] = *(const u32x4*)(src + 32); kr[rep][2] = *(const u32x4*)(src + 64); kr[rep][3] = *(const u32x4*)(src + 96); } }
; #pragma unroll
;         for (int a = 0; a < 2; ++a) { nacc[a] *= decay;
; #pragma unroll
;             for (int v = 0; v < 4; ++v) acc[a][v] *= decay; }
	ds_read_b64 v[0:1], v91 offset:512
	v_mov_b32_e32 v2, s3
	ds_read_b32 v28, v2
	v_lshlrev_b32_e32 v2, 16, v36
	v_mfma_f32_16x16x32_bf16 v[16:19], v[52:55], v[114:117], v[48:51]
	s_waitcnt lgkmcnt(1)
	v_mul_f32_e32 v0, v0, v2
	v_and_b32_e32 v2, 0xffff0000, v36
	v_mul_f32_e32 v1, v1, v2
	v_cvt_pk_bf16_f32 v36, v0, v1
	ds_read_b64 v[0:1], v91 offset:520
	v_lshlrev_b32_e32 v2, 16, v37
	v_cndmask_b32_e64 v51, 0, v121, s[0:1]
	v_cndmask_b32_e64 v50, 0, v120, s[0:1]
	v_cndmask_b32_e64 v49, 0, v119, s[0:1]
	s_waitcnt lgkmcnt(0)
	v_mul_f32_e32 v0, v0, v2
	v_and_b32_e32 v2, 0xffff0000, v37
	v_mul_f32_e32 v1, v1, v2
	v_cvt_pk_bf16_f32 v37, v0, v1
	ds_read_b64 v[0:1], v91 offset:528
	v_lshlrev_b32_e32 v2, 16, v38
	v_cndmask_b32_e64 v48, 0, v118, s[0:1]
	v_mfma_f32_16x16x32_bf16 v[134:137], v[52:55], v[58:61], v[24:27]
	v_mul_f32_e64 v18, v18, v28
	v_mul_f32_e64 v19, v19, v28
	s_waitcnt lgkmcnt(0)
	v_mul_f32_e32 v0, v0, v2
	v_and_b32_e32 v2, 0xffff0000, v38
	v_mfma_f32_16x16x32_bf16 v[40:43], v[52:55], v[74:77], v[40:43]
	v_mul_f32_e32 v1, v1, v2
	v_cvt_pk_bf16_f32 v38, v0, v1
	v_pk_mul_f32 v[16:17], v[16:17], v[28:29] op_sel_hi:[1,0]
	v_mfma_f32_16x16x32_bf16 v[24:27], v[52:55], v[122:125], v[70:73]
	s_lshl_b32 s3, s46, 4
	s_nop 3
	v_pk_mul_f32 v[42:43], v[42:43], v[28:29] op_sel_hi:[1,0]
	v_pk_mul_f32 v[40:41], v[40:41], v[28:29] op_sel_hi:[1,0]
	v_mfma_f32_16x16x32_bf16 v[52:55], v[52:55], v[48:51], v[4:7]
	s_or_b32 s12, s11, s3
	v_pk_mul_f32 v[26:27], v[26:27], v[28:29] op_sel_hi:[1,0]
	v_pk_mul_f32 v[24:25], v[24:25], v[28:29] op_sel_hi:[1,0]
	ds_read_b64 v[4:5], v91 offset:536
	v_lshlrev_b32_e32 v6, 16, v39
	v_mfma_f32_16x16x32_bf16 v[0:3], v[20:23], v[58:61], v[8:11]
	s_lshl_b32 s11, s12, 2
	s_or_b32 s14, s11, s25
	s_waitcnt lgkmcnt(0)
	v_mul_f32_e32 v4, v4, v6
	v_and_b32_e32 v6, 0xffff0000, v39
	v_mul_f32_e32 v5, v5, v6
	v_cvt_pk_bf16_f32 v39, v4, v5
	ds_write_b128 v106, v[36:39]
	ds_read_b64 v[8:9], v91 offset:512
	v_lshlrev_b32_e32 v10, 16, v66
	v_mfma_f32_16x16x32_bf16 v[4:7], v[20:23], v[74:77], v[12:15]
	v_mul_f32_e64 v2, v2, v28
	v_mul_f32_e64 v3, v3, v28
	v_pk_mul_f32 v[0:1], v[0:1], v[28:29] op_sel_hi:[1,0]
	s_waitcnt lgkmcnt(0)
	v_mul_f32_e32 v8, v8, v10
	v_and_b32_e32 v10, 0xffff0000, v66
	v_mul_f32_e32 v9, v9, v10
	v_cvt_pk_bf16_f32 v36, v8, v9
	ds_read_b64 v[12:13], v91 offset:520
	v_lshlrev_b32_e32 v14, 16, v67
	v_mfma_f32_16x16x32_bf16 v[8:11], v[20:23], v[114:117], v[44:47]
	v_mul_f32_e64 v6, v6, v28
	v_mul_f32_e64 v7, v7, v28
	v_pk_mul_f32 v[4:5], v[4:5], v[28:29] op_sel_hi:[1,0]
	s_waitcnt lgkmcnt(0)
	v_mul_f32_e32 v12, v12, v14
	v_and_b32_e32 v14, 0xffff0000, v67
	v_mul_f32_e32 v13, v13, v14
	v_cvt_pk_bf16_f32 v37, v12, v13
	ds_read_b64 v[38:39], v91 offset:528
	v_mfma_f32_16x16x32_bf16 v[12:15], v[20:23], v[122:125], v[32:35]
	v_mul_f32_e64 v10, v10, v28
	v_mul_f32_e64 v11, v11, v28
	v_pk_mul_f32 v[8:9], v[8:9], v[28:29] op_sel_hi:[1,0]
	s_ashr_i32 s15, s14, 31
	v_and_b32_e32 v32, 0xffff0000, v68
	s_waitcnt lgkmcnt(0)
	v_mul_f32_e32 v32, v39, v32
	v_mul_f32_e32 v31, v38, v31
	v_cvt_pk_bf16_f32 v38, v31, v32
	ds_read_b64 v[32:33], v91 offset:536
	v_lshlrev_b32_e32 v31, 16, v69
	v_mfma_f32_16x16x32_bf16 v[20:23], v[20:23], v[48:51], v[62:65]
	v_mul_f32_e64 v14, v14, v28
	v_mul_f32_e64 v15, v15, v28
	v_pk_mul_f32 v[12:13], v[12:13], v[28:29] op_sel_hi:[1,0]
	s_waitcnt lgkmcnt(0)
	v_mul_f32_e32 v31, v32, v31
	v_and_b32_e32 v32, 0xffff0000, v69
	v_mul_f32_e32 v32, v33, v32
	v_cvt_pk_bf16_f32 v39, v31, v32
	s_waitcnt vmcnt(7)
	v_and_b32_e32 v31, 0xffff, v126
	s_waitcnt vmcnt(5)
	v_lshl_or_b32 v32, v92, 16, v31
	s_waitcnt vmcnt(4)
	v_and_b32_e32 v31, 0xffff, v130
	v_lshl_or_b32 v33, v96, 16, v31
	v_lshrrev_b32_e32 v31, 16, v126
	v_and_or_b32 v34, v92, s39, v31
	v_lshrrev_b32_e32 v31, 16, v130
	v_and_or_b32 v35, v96, s39, v31
	v_and_b32_e32 v31, 0xffff, v127
	ds_write_b128 v107, v[36:39]
	ds_write2_b64 v108, v[32:33], v[34:35] offset1:34
	v_lshl_or_b32 v32, v93, 16, v31
	v_and_b32_e32 v31, 0xffff, v131
	v_lshl_or_b32 v33, v97, 16, v31
	v_lshrrev_b32_e32 v31, 16, v127
	v_and_or_b32 v34, v93, s39, v31
	v_lshrrev_b32_e32 v31, 16, v131
	v_and_or_b32 v35, v97, s39, v31
	v_and_b32_e32 v31, 0xffff, v128
	ds_write2_b64 v108, v[32:33], v[34:35] offset0:68 offset1:102
	v_lshl_or_b32 v32, v94, 16, v31
	v_and_b32_e32 v31, 0xffff, v132
	v_lshl_or_b32 v33, v98, 16, v31
	v_lshrrev_b32_e32 v31, 16, v128
	v_and_or_b32 v34, v94, s39, v31
	v_lshrrev_b32_e32 v31, 16, v132
	v_and_or_b32 v35, v98, s39, v31
	v_and_b32_e32 v31, 0xffff, v129
	ds_write2_b64 v108, v[32:33], v[34:35] offset0:136 offset1:170
	v_lshl_or_b32 v32, v95, 16, v31
	v_and_b32_e32 v31, 0xffff, v133
	v_lshl_or_b32 v33, v99, 16, v31
	v_lshrrev_b32_e32 v31, 16, v129
	v_and_or_b32 v34, v95, s39, v31
	v_lshrrev_b32_e32 v31, 16, v133
	v_and_or_b32 v35, v99, s39, v31
	s_waitcnt vmcnt(3)
	v_and_b32_e32 v31, 0xffff, v138
	ds_write2_b64 v108, v[32:33], v[34:35] offset0:204 offset1:238
	s_waitcnt vmcnt(2)
	v_lshl_or_b32 v32, v142, 16, v31
	s_waitcnt vmcnt(1)
	v_and_b32_e32 v31, 0xffff, v146
	s_waitcnt vmcnt(0)
	v_lshl_or_b32 v33, v150, 16, v31
	v_lshrrev_b32_e32 v31, 16, v138
	v_and_or_b32 v34, v142, s39, v31
	v_lshrrev_b32_e32 v31, 16, v146
	v_and_or_b32 v35, v150, s39, v31
	v_and_b32_e32 v31, 0xffff, v139
	ds_write2_b64 v109, v[32:33], v[34:35] offset1:34
	v_lshl_or_b32 v32, v143, 16, v31
	v_and_b32_e32 v31, 0xffff, v147
	v_lshl_or_b32 v33, v151, 16, v31
	v_lshrrev_b32_e32 v31, 16, v139
	v_and_or_b32 v34, v143, s39, v31
	v_lshrrev_b32_e32 v31, 16, v147
	v_and_or_b32 v35, v151, s39, v31
	v_and_b32_e32 v31, 0xffff, v140
	ds_write2_b64 v109, v[32:33], v[34:35] offset0:68 offset1:102
	v_lshl_or_b32 v32, v144, 16, v31
	v_and_b32_e32 v31, 0xffff, v148
	v_lshl_or_b32 v33, v152, 16, v31
	v_lshrrev_b32_e32 v31, 16, v140
	v_and_or_b32 v34, v144, s39, v31
	v_lshrrev_b32_e32 v31, 16, v148
	v_and_or_b32 v35, v152, s39, v31
	v_and_b32_e32 v31, 0xffff, v141
	ds_write2_b64 v109, v[32:33], v[34:35] offset0:136 offset1:170
	v_lshl_or_b32 v32, v145, 16, v31
	v_and_b32_e32 v31, 0xffff, v149
	v_lshl_or_b32 v33, v153, 16, v31
	v_lshrrev_b32_e32 v31, 16, v141
	v_and_or_b32 v34, v145, s39, v31
	v_lshrrev_b32_e32 v31, 16, v149
	v_and_or_b32 v35, v153, s39, v31
	ds_write2_b64 v109, v[32:33], v[34:35] offset0:204 offset1:238
	s_waitcnt lgkmcnt(0)
	s_barrier
; #define LAS __attribute__((address_space(3)))
; __device__ void passA(const Params& p, LAS unsigned char* lds, int wg) {
;     ...
;         if (st + 1 < 17) {
;             bool ic2; int ci2; const bf16_t* Kb2; const bf16_t* Vb2; passA_chunk(p, st + 1, b, h, dir, vs, ic2, ci2, Kb2, Vb2);
; #pragma unroll
;             for (int rep = 0; rep < 2; ++rep) { const int it = tid + rep * 512;
;                 vr[rep] = *(const u32x4*)(Vb2 + (size_t)it * 8);
;                 const int sq = (it & 15) | (((it >> 6) & 1) << 4), ko = ((it >> 4) & 3) | ((it >> 7) << 2); const bf16_t* src = Kb2 + (size_t)((sq >> 2) * 8 + (ko >> 2)) * 512 + ((sq & 3) * 16 + (ko & 3)) * 8;
;                 kr[rep][0] = *(const u32x4*)src; kr[rep][1] = *(const u32x4*)(src + 32); kr[rep][2] = *(const u32x4*)(src + 64); kr[rep][3] = *(const u32x4*)(src + 96); } }
; #pragma unroll
;         for (int a = 0; a < 2; ++a) { nacc[a] *= decay;
; #pragma unroll
;             for (int v = 0; v < 4; ++v) acc[a][v] *= decay; }
; #pragma unroll
;         for (int ks = 0; ks < 4; ++ks) { bf16x8 kf[2], vf[4];
; #pragma unroll
;             for (int kt = 0; kt < 2; ++kt) kf[kt] = *(const LAS bf16x8*)(Kt + (wid * 32 + 8 * (fr >> 2) + 4 * kt + (fr & 3)) * 136 + ks * 32 + fq * 8);
; #pragma unroll
;             for (int vt = 0; vt < 4; ++vt) vf[vt] = *(const LAS bf16x8*)(Ve + (vt * 16 + fr) * 136 + ks * 32 + fq * 8);
;             bf16x8 ef = *(const LAS bf16x8*)(eB + st * 128 + ks * 32 + fq * 8);
;             if (fr != 0) ef = (bf16x8){0, 0, 0, 0, 0, 0, 0, 0};
; #pragma unroll
;             for (int kt = 0; kt < 2; ++kt) {
; #pragma unroll
;                 for (int vt = 0; vt < 4; ++vt) acc[kt][vt] = __builtin_amdgcn_mfma_f32_16x16x32_bf16(kf[kt], vf[vt], acc[kt][vt], 0, 0, 0);
;                 nacc[kt] = __builtin_amdgcn_mfma_f32_16x16x32_bf16(kf[kt], ef, nacc[kt], 0, 0, 0); } }
	ds_read_b128 v[44:47], v110
	ds_read_b128 v[48:51], v29
	v_pk_mul_f32 v[34:35], v[54:55], v[28:29] op_sel_hi:[1,0]
	v_pk_mul_f32 v[32:33], v[52:53], v[28:29] op_sel_hi:[1,0]
	ds_read_b128 v[52:55], v29 offset:4352
	ds_read_b128 v[58:61], v110 offset:64
	ds_read_b128 v[62:65], v29 offset:64
	ds_read_b128 v[66:69], v110 offset:1088
	ds_read_b128 v[70:73], v29 offset:8704
	ds_read_b128 v[74:77], v29 offset:4416
	ds_read_b128 v[92:95], v30 offset:256
	ds_read_b128 v[96:99], v29 offset:13056
	ds_read_b128 v[114:117], v29 offset:8768
	v_pk_mul_f32 v[38:39], v[136:137], v[28:29] op_sel_hi:[1,0]
	v_pk_mul_f32 v[36:37], v[134:135], v[28:29] op_sel_hi:[1,0]
	s_waitcnt lgkmcnt(2)
	v_cndmask_b32_e64 v95, 0, v95, s[0:1]
	v_cndmask_b32_e64 v94, 0, v94, s[0:1]
	v_cndmask_b32_e64 v93, 0, v93, s[0:1]
	v_cndmask_b32_e64 v92, 0, v92, s[0:1]
	v_mfma_f32_16x16x32_bf16 v[36:39], v[44:47], v[48:51], v[36:39]
	ds_read_b128 v[118:121], v30 offset:320
	ds_read_b128 v[122:125], v29 offset:13120
	v_pk_mul_f32 v[22:23], v[22:23], v[28:29] op_sel_hi:[1,0]
	v_mfma_f32_16x16x32_bf16 v[40:43], v[44:47], v[52:55], v[40:43]
	v_mul_f32_e64 v20, v20, v28
	v_mul_f32_e64 v21, v21, v28
	s_lshl_b64 s[14:15], s[14:15], 16
	s_add_u32 s14, s30, s14
	v_mfma_f32_16x16x32_bf16 v[16:19], v[44:47], v[70:73], v[16:19]
	s_addc_u32 s15, s31, s15
	s_ashr_i32 s13, s12, 31
	s_lshl_b64 s[12:13], s[12:13], 18
	s_waitcnt lgkmcnt(3)
	v_mfma_f32_16x16x32_bf16 v[24:27], v[44:47], v[96:99], v[24:27]
	s_add_u32 s11, s16, s12
	s_addc_u32 s13, s17, s13
	s_add_u32 s12, s11, s10
	v_mfma_f32_16x16x32_bf16 v[32:35], v[44:47], v[92:95], v[32:35]
	ds_read_b128 v[44:47], v110 offset:1152
	s_addc_u32 s13, s13, 0
	v_ashrrev_i32_e32 v91, 31, v90
	v_mfma_f32_16x16x32_bf16 v[4:7], v[66:69], v[52:55], v[4:7]
	ds_read_b128 v[52:55], v110 offset:128
	v_mfma_f32_16x16x32_bf16 v[0:3], v[66:69], v[48:51], v[0:3]
	s_waitcnt lgkmcnt(3)
	v_cndmask_b32_e64 v51, 0, v121, s[0:1]
	v_cndmask_b32_e64 v50, 0, v120, s[0:1]
	v_cndmask_b32_e64 v49, 0, v119, s[0:1]
	v_mfma_f32_16x16x32_bf16 v[8:11], v[66:69], v[70:73], v[8:11]
	v_cndmask_b32_e64 v48, 0, v118, s[0:1]
	v_mfma_f32_16x16x32_bf16 v[12:15], v[66:69], v[96:99], v[12:15]
	v_mfma_f32_16x16x32_bf16 v[20:23], v[66:69], v[92:95], v[20:23]
	v_mfma_f32_16x16x32_bf16 v[36:39], v[58:61], v[62:65], v[36:39]
	v_mfma_f32_16x16x32_bf16 v[40:43], v[58:61], v[74:77], v[40:43]
	v_mfma_f32_16x16x32_bf16 v[16:19], v[58:61], v[114:117], v[16:19]
	s_waitcnt lgkmcnt(2)
	v_mfma_f32_16x16x32_bf16 v[24:27], v[58:61], v[122:125], v[24:27]
	v_mfma_f32_16x16x32_bf16 v[32:35], v[58:61], v[48:51], v[32:35]
	ds_read_b128 v[58:61], v29 offset:128
	s_waitcnt lgkmcnt(2)
	v_mfma_f32_16x16x32_bf16 v[0:3], v[44:47], v[62:65], v[0:3]
	v_mfma_f32_16x16x32_bf16 v[4:7], v[44:47], v[74:77], v[4:7]
	v_mfma_f32_16x16x32_bf16 v[8:11], v[44:47], v[114:117], v[8:11]
	v_mfma_f32_16x16x32_bf16 v[12:15], v[44:47], v[122:125], v[12:15]
	v_mfma_f32_16x16x32_bf16 v[20:23], v[44:47], v[48:51], v[20:23]
	ds_read_b128 v[44:47], v29 offset:4480
	ds_read_b128 v[48:51], v110 offset:192
	ds_read_b128 v[92:95], v29 offset:192
	ds_read_b128 v[62:65], v110 offset:1216
	ds_read_b128 v[66:69], v29 offset:8832
	ds_read_b128 v[96:99], v29 offset:4544
	ds_read_b128 v[70:73], v30 offset:384
	ds_read_b128 v[74:77], v29 offset:13184
	ds_read_b128 v[114:117], v29 offset:8896
	ds_read_b128 v[118:121], v30 offset:448
	ds_read_b128 v[122:125], v29 offset:13248
	s_waitcnt lgkmcnt(11)
	v_mfma_f32_16x16x32_bf16 v[36:39], v[52:55], v[58:61], v[36:39]
	s_waitcnt lgkmcnt(4)
	v_cndmask_b32_e64 v31, 0, v73, s[0:1]
	v_cndmask_b32_e64 v30, 0, v72, s[0:1]
	v_cndmask_b32_e64 v29, 0, v71, s[0:1]
	v_cndmask_b32_e64 v28, 0, v70, s[0:1]
	v_mfma_f32_16x16x32_bf16 v[40:43], v[52:55], v[44:47], v[40:43]
	s_waitcnt lgkmcnt(1)
	v_cndmask_b32_e64 v121, 0, v121, s[0:1]
	v_cndmask_b32_e64 v120, 0, v120, s[0:1]
	v_cndmask_b32_e64 v119, 0, v119, s[0:1]
	v_mfma_f32_16x16x32_bf16 v[16:19], v[52:55], v[66:69], v[16:19]
	v_cndmask_b32_e64 v118, 0, v118, s[0:1]
	ds_read_b128 v[126:129], v110 offset:1280
	v_mfma_f32_16x16x32_bf16 v[24:27], v[52:55], v[74:77], v[24:27]
	v_mfma_f32_16x16x32_bf16 v[32:35], v[52:55], v[28:31], v[32:35]
	v_mfma_f32_16x16x32_bf16 v[138:141], v[62:65], v[28:31], v[20:23]
	v_lshl_add_u64 v[28:29], s[14:15], 0, v[82:83]
	s_mov_b64 s[14:15], 0x2000
	v_mfma_f32_16x16x32_bf16 v[52:55], v[62:65], v[58:61], v[0:3]
	v_lshl_add_u64 v[20:21], v[28:29], 0, v[86:87]
	v_lshl_add_u64 v[22:23], s[12:13], 0, v[84:85]
	v_mfma_f32_16x16x32_bf16 v[134:137], v[62:65], v[74:77], v[12:15]
	v_lshl_add_u64 v[0:1], s[12:13], 0, v[80:81]
	s_add_u32 s12, s70, 0xbc00000
	s_addc_u32 s13, s71, 0
	v_mfma_f32_16x16x32_bf16 v[72:75], v[48:51], v[92:95], v[36:39]
	s_cmp_lt_i32 s26, 32
	s_mov_b32 s26, 0xffff
	s_nop 0
	v_lshl_add_u64 v[36:37], v[28:29], 0, v[88:89]
	v_mfma_f32_16x16x32_bf16 v[58:61], v[62:65], v[44:47], v[4:7]
	v_mfma_f32_16x16x32_bf16 v[130:133], v[62:65], v[66:69], v[8:11]
	s_nop 2
	global_load_dwordx4 v[8:11], v[0:1], off
	s_nop 0
	global_load_dwordx4 v[0:3], v[20:21], off
	global_load_dwordx4 v[4:7], v[20:21], off offset:64
	global_load_dwordx4 v[12:15], v[20:21], off offset:128
	v_mfma_f32_16x16x32_bf16 v[68:71], v[48:51], v[96:99], v[40:43]
	v_mfma_f32_16x16x32_bf16 v[64:67], v[48:51], v[114:117], v[16:19]
	s_nop 2
	global_load_dwordx4 v[16:19], v[20:21], off offset:192
	s_nop 0
	global_load_dwordx4 v[20:23], v[22:23], off
	s_waitcnt lgkmcnt(1)
	v_mfma_f32_16x16x32_bf16 v[40:43], v[48:51], v[122:125], v[24:27]
	s_nop 2
	global_load_dwordx4 v[24:27], v[36:37], off
	global_load_dwordx4 v[28:31], v[36:37], off offset:64
	v_mfma_f32_16x16x32_bf16 v[76:79], v[48:51], v[118:121], v[32:35]
	s_nop 2
	global_load_dwordx4 v[32:35], v[36:37], off offset:128
	s_nop 0
	global_load_dwordx4 v[36:39], v[36:37], off offset:192
	s_waitcnt lgkmcnt(0)
	s_barrier
; __device__ __forceinline__ unsigned cvt_pk_bf16(float lo, float hi) { unsigned r; asm volatile("v_cvt_pk_bf16_f32 %0, %1, %2" : "=v"(r) : "v"(lo), "v"(hi)); return r; }
; __device__ void passA(const Params& p, LAS unsigned char* lds, int wg) {
;     ...
;         bool isctx; int ci; const bf16_t* Kb; const bf16_t* Vb; passA_chunk(p, st, b, h, dir, vs, isctx, ci, Kb, Vb);
;         if (!isctx) {
;             bf16_t* cs = cst_ptr(p, sid, ci);
; #pragma unroll
;             for (int vt = 0; vt < 4; ++vt) { u32x4 w; w.x = cvt_pk_bf16(acc[0][vt][0], acc[0][vt][1]); w.y = cvt_pk_bf16(acc[0][vt][2], acc[0][vt][3]);
;                 w.z = cvt_pk_bf16(acc[1][vt][0], acc[1][vt][1]); w.w = cvt_pk_bf16(acc[1][vt][2], acc[1][vt][3]);
;                 __builtin_nontemporal_store(w, (u32x4*)(cs + (size_t)((vs * 4 + vt) * 8 + wid) * 512 + (fr * 4 + fq) * 8)); }
;             if (vs == 0) { if (fr == 0) { float* np = (float*)(p.ws + OFF_NST) + (size_t)(sid * 16 + ci) * 256 + wid * 32 + fq * 8; *(f32x4*)np = nacc[0]; *(f32x4*)(np + 4) = nacc[1]; }
;                 if (tid == 0) ((float*)(p.ws + OFF_MST))[sid * 16 + ci] = mprevA[st]; }
	v_mfma_f32_16x16x32_bf16 v[44:47], v[126:129], v[92:95], v[52:55]
	v_lshl_add_u32 v92, s34, 5, v56
	v_ashrrev_i32_e32 v93, 31, v92
	v_lshlrev_b64 v[92:93], 10, v[92:93]
	v_lshl_add_u64 v[94:95], v[92:93], 0, s[14:15]
	s_mov_b64 s[14:15], 0x4000
	v_mfma_f32_16x16x32_bf16 v[48:51], v[126:129], v[96:99], v[58:61]
	v_lshl_add_u64 v[96:97], v[92:93], 0, s[14:15]
	s_mov_b64 s[14:15], 0x6000
	v_lshl_add_u64 v[98:99], v[92:93], 0, s[14:15]
	s_cselect_b32 s15, s69, s13
	s_cselect_b32 s14, s68, s12
	s_add_u32 s41, s16, s10
	s_addc_u32 s46, s17, 0
	v_mfma_f32_16x16x32_bf16 v[52:55], v[126:129], v[114:117], v[130:133]
	v_and_b32_e32 v114, 24, v57
	s_add_u32 s16, s70, 0xfd20000
	v_lshlrev_b32_e32 v101, 1, v114
	v_mfma_f32_16x16x32_bf16 v[56:59], v[126:129], v[122:125], v[134:137]
	s_addc_u32 s17, s71, 0
	v_mul_u32_u24_e32 v115, 0x110, v100
	v_lshl_or_b32 v100, v100, 6, v101
	v_mfma_f32_16x16x32_bf16 v[60:63], v[126:129], v[118:121], v[138:141]
	v_mov_b32_e32 v101, v83
	v_lshl_add_u64 v[90:91], v[90:91], 2, s[16:17]
	v_lshlrev_b32_e32 v82, 2, v114
	v_lshl_add_u64 v[100:101], s[14:15], 0, v[100:101]
	v_lshl_add_u64 v[90:91], v[90:91], 0, v[82:83]
	s_add_u32 s14, s70, 0xfe20000
	v_lshlrev_b32_e32 v82, 5, v112
	s_movk_i32 s10, 0x180
	s_addc_u32 s15, s71, 0
	v_and_or_b32 v112, v111, s10, v82
	v_add_u32_e32 v111, v113, v115
	s_mov_b32 s54, 0x05040100
	s_mov_b32 s55, 0x07060302
	s_branch .LBB0_392

; #define LAS __attribute__((address_space(3)))
; __device__ __forceinline__ float bf_lo(unsigned w) { return __uint_as_float(w << 16); }
; __device__ __forceinline__ float bf_hi(unsigned w) { return __uint_as_float(w & 0xffff0000u); }
; __device__ void passA(const Params& p, LAS unsigned char* lds, int wg) {
;     ...
;         const LAS float* e_s = eA + st * 128; const float decay = decayA[st];
; #pragma unroll
;         for (int rep = 0; rep < 2; ++rep) { const int it = tid + rep * 512; const int v = (it >> 8) * 16 + ((it >> 2) & 15), sg = ((it >> 6) & 3) * 32 + (it & 3) * 8;
;             const u32x4 raw = vr[rep];
;             u32x4 w; w.x = cvt_pk_bf16(bf_lo(raw.x) * e_s[sg], bf_hi(raw.x) * e_s[sg + 1]); w.y = cvt_pk_bf16(bf_lo(raw.y) * e_s[sg + 2], bf_hi(raw.y) * e_s[sg + 3]);
;             w.z = cvt_pk_bf16(bf_lo(raw.z) * e_s[sg + 4], bf_hi(raw.z) * e_s[sg + 5]); w.w = cvt_pk_bf16(bf_lo(raw.w) * e_s[sg + 6], bf_hi(raw.w) * e_s[sg + 7]);
;             *(LAS u32x4*)(Ve + v * 136 + sg) = w; }
; #pragma unroll
;         for (int rep = 0; rep < 2; ++rep) { const int it = tid + rep * 512; const int sq = (it & 15) | (((it >> 6) & 1) << 4), ko = ((it >> 4) & 3) | ((it >> 7) << 2);
;             const u32x4 r0 = kr[rep][0], r1 = kr[rep][1], r2 = kr[rep][2], r3 = kr[rep][3];
;             LAS bf16_t* dst = Kt + (ko * 8) * 136 + sq * 4;
;     ...
;             TRW(0, r0.x, r1.x, r2.x, r3.x, 0) TRW(1, r0.x, r1.x, r2.x, r3.x, 1) TRW(2, r0.y, r1.y, r2.y, r3.y, 0) TRW(3, r0.y, r1.y, r2.y, r3.y, 1)
;             TRW(4, r0.z, r1.z, r2.z, r3.z, 0) TRW(5, r0.z, r1.z, r2.z, r3.z, 1) TRW(6, r0.w, r1.w, r2.w, r3.w, 0) TRW(7, r0.w, r1.w, r2.w, r3.w, 1)
;     ...
;         }
;         __syncthreads();
;         if (st + 1 < 17) {
;             bool ic2; int ci2; const bf16_t* Kb2; const bf16_t* Vb2; passA_chunk(p, st + 1, b, h, dir, vs, ic2, ci2, Kb2, Vb2);
; #pragma unroll
;             for (int rep = 0; rep < 2; ++rep) { const int it = tid + rep * 512;
;                 vr[rep] = *(const u32x4*)(Vb2 + (size_t)it * 8);
;                 const int sq = (it & 15) | (((it >> 6) & 1) << 4), ko = ((it >> 4) & 3) | ((it >> 7) << 2); const bf16_t* src = Kb2 + (size_t)((sq >> 2) * 8 + (ko >> 2)) * 512 + ((sq & 3) * 16 + (ko & 3)) * 8;
;                 kr[rep][0] = *(const u32x4*)src; kr[rep][1] = *(const u32x4*)(src + 32); kr[rep][2] = *(const u32x4*)(src + 64); kr[rep][3] = *(const u32x4*)(src + 96); } }
.LBB0_394:
	v_add_u32_e32 v120, 0x15800, v112
	ds_read_b128 v[124:127], v120
	ds_read_b128 v[128:131], v120 offset:16
	s_add_i32 s10, s40, 0
	s_add_i32 s10, s10, 0x17908
	v_mov_b32_e32 v82, s10
	ds_read_b32 v82, v82
	s_cmp_gt_u32 s27, 15
	s_waitcnt vmcnt(13)
	v_lshlrev_b32_e32 v132, 16, v8
	v_and_b32_e32 v133, 0xffff0000, v8
	v_lshlrev_b32_e32 v134, 16, v9
	v_and_b32_e32 v135, 0xffff0000, v9
	v_lshlrev_b32_e32 v136, 16, v10
	v_and_b32_e32 v137, 0xffff0000, v10
	v_lshlrev_b32_e32 v138, 16, v11
	v_and_b32_e32 v139, 0xffff0000, v11
	s_waitcnt lgkmcnt(1)
	v_pk_mul_f32 v[132:133], v[124:125], v[132:133]
	v_pk_mul_f32 v[134:135], v[126:127], v[134:135]
	v_pk_mul_f32 v[136:137], v[128:129], v[136:137]
	v_pk_mul_f32 v[138:139], v[130:131], v[138:139]
	v_cvt_pk_bf16_f32 v114, v132, v133
	v_cvt_pk_bf16_f32 v115, v134, v135
	v_cvt_pk_bf16_f32 v116, v136, v137
	v_cvt_pk_bf16_f32 v117, v138, v139
	ds_write_b128 v106, v[114:117]
	s_waitcnt vmcnt(8)
	v_lshlrev_b32_e32 v132, 16, v20
	v_and_b32_e32 v133, 0xffff0000, v20
	v_lshlrev_b32_e32 v134, 16, v21
	v_and_b32_e32 v135, 0xffff0000, v21
	v_lshlrev_b32_e32 v136, 16, v22
	v_and_b32_e32 v137, 0xffff0000, v22
	v_lshlrev_b32_e32 v138, 16, v23
	v_and_b32_e32 v139, 0xffff0000, v23
	v_pk_mul_f32 v[132:133], v[124:125], v[132:133]
	v_pk_mul_f32 v[134:135], v[126:127], v[134:135]
	v_pk_mul_f32 v[136:137], v[128:129], v[136:137]
	v_pk_mul_f32 v[138:139], v[130:131], v[138:139]
	v_cvt_pk_bf16_f32 v114, v132, v133
	v_cvt_pk_bf16_f32 v115, v134, v135
	v_cvt_pk_bf16_f32 v116, v136, v137
	v_cvt_pk_bf16_f32 v117, v138, v139
	ds_write_b128 v107, v[114:117]
	v_perm_b32 v114, v4, v0, s54
	v_perm_b32 v115, v16, v12, s54
	v_perm_b32 v116, v4, v0, s55
	v_perm_b32 v117, v16, v12, s55
	ds_write2_b64 v108, v[114:115], v[116:117] offset1:34
	v_perm_b32 v114, v5, v1, s54
	v_perm_b32 v115, v17, v13, s54
	v_perm_b32 v116, v5, v1, s55
	v_perm_b32 v117, v17, v13, s55
	ds_write2_b64 v108, v[114:115], v[116:117] offset0:68 offset1:102
	v_perm_b32 v114, v6, v2, s54
	v_perm_b32 v115, v18, v14, s54
	v_perm_b32 v116, v6, v2, s55
	v_perm_b32 v117, v18, v14, s55
	ds_write2_b64 v108, v[114:115], v[116:117] offset0:136 offset1:170
	v_perm_b32 v114, v7, v3, s54
	v_perm_b32 v115, v19, v15, s54
	v_perm_b32 v116, v7, v3, s55
	v_perm_b32 v117, v19, v15, s55
	s_waitcnt vmcnt(6)
	ds_write2_b64 v108, v[114:115], v[116:117] offset0:204 offset1:238
	v_perm_b32 v114, v28, v24, s54
	s_waitcnt vmcnt(4)
	v_perm_b32 v115, v36, v32, s54
	v_perm_b32 v116, v28, v24, s55
	v_perm_b32 v117, v36, v32, s55
	ds_write2_b64 v109, v[114:115], v[116:117] offset1:34
	v_perm_b32 v114, v29, v25, s54
	v_perm_b32 v115, v37, v33, s54
	v_perm_b32 v116, v29, v25, s55
	v_perm_b32 v117, v37, v33, s55
	ds_write2_b64 v109, v[114:115], v[116:117] offset0:68 offset1:102
	v_perm_b32 v114, v30, v26, s54
	v_perm_b32 v115, v38, v34, s54
	v_perm_b32 v116, v30, v26, s55
	v_perm_b32 v117, v38, v34, s55
	ds_write2_b64 v109, v[114:115], v[116:117] offset0:136 offset1:170
	v_perm_b32 v114, v31, v27, s54
	v_perm_b32 v115, v39, v35, s54
	v_perm_b32 v116, v31, v27, s55
	v_perm_b32 v117, v39, v35, s55
	ds_write2_b64 v109, v[114:115], v[116:117] offset0:204 offset1:238
	s_waitcnt lgkmcnt(0)
	s_barrier
	s_cbranch_scc1 .LBB0_391
	s_add_i32 s47, s27, -1
	s_and_b64 s[10:11], s[8:9], exec
	s_cselect_b32 s10, s47, s28
	s_add_i32 s10, s10, s3
	s_lshl_b32 s11, s10, 2
	s_or_b32 s48, s11, s25
	s_ashr_i32 s49, s48, 31
	s_ashr_i32 s11, s10, 31
	s_lshl_b64 s[48:49], s[48:49], 16
	s_lshl_b64 s[10:11], s[10:11], 18
	s_add_u32 s10, s41, s10
	s_addc_u32 s11, s46, s11
	v_lshl_add_u64 v[24:25], v[102:103], 0, s[48:49]
	v_lshl_add_u64 v[0:1], s[10:11], 0, v[80:81]
	v_lshl_add_u64 v[16:17], v[24:25], 0, v[86:87]
	v_lshl_add_u64 v[20:21], s[10:11], 0, v[84:85]
	v_lshl_add_u64 v[36:37], v[24:25], 0, v[88:89]
	global_load_dwordx4 v[8:11], v[0:1], off
	s_nop 0
	global_load_dwordx4 v[0:3], v[16:17], off
	global_load_dwordx4 v[4:7], v[16:17], off offset:64
	global_load_dwordx4 v[12:15], v[16:17], off offset:128
	s_nop 0
	global_load_dwordx4 v[16:19], v[16:17], off offset:192
	s_nop 0
	global_load_dwordx4 v[20:23], v[20:21], off
	s_nop 0
	global_load_dwordx4 v[24:27], v[36:37], off
	global_load_dwordx4 v[28:31], v[36:37], off offset:64
	global_load_dwordx4 v[32:35], v[36:37], off offset:128
	s_nop 0
	global_load_dwordx4 v[36:39], v[36:37], off offset:192
	s_branch .LBB0_391
